# global grid barriers: the XCD leader increments the generation (releases its XCD) before invalidating its own L1
# speedup vs baseline: 1.0618x; 1.0032x over previous
.LBB0_58:
	s_or_b64 exec, exec, s[4:5]
	s_mov_b64 s[4:5], exec
	v_mbcnt_lo_u32_b32 v2, s4, 0
	v_mbcnt_hi_u32_b32 v2, s5, v2
	v_cmp_eq_u32_e32 vcc, 0, v2
	s_waitcnt vmcnt(0)
	s_and_saveexec_b64 s[6:7], vcc
	s_cbranch_execz .LBB0_60
	s_bcnt1_i32_b64 s4, s[4:5]
	v_mov_b32_e32 v2, s4
	v_readlane_b32 s4, v253, 8
	v_readlane_b32 s5, v253, 9
	s_nop 4
	global_atomic_add v131, v2, s[4:5]
.LBB0_60:
	s_or_b64 exec, exec, s[6:7]
	buffer_inv sc1
	s_waitcnt vmcnt(0)
